# speedup vs baseline: 1.0134x; 1.0028x over previous
; #define VB() ([&]() { int b_ = bid; asm volatile("" : "+s"(b_)); return (G % 8 == 0) ? (b_ % 8) * (G / 8) + b_ / 8 : b_; }())
; #define PHASE(k, kind, ...) do { if (EN(kind) && IN(k)) { for (int rep_ = (((REPMASK) >> (k)) & 1u) ? 0 : 1; rep_ < 2; ++rep_) { const bool dry = (rep_ == 0); (void)dry; __VA_ARGS__ if (rep_ == 0 && p.coop) GSYNC(k); } } SEAM(k); } while (0)
; __global__ void __launch_bounds__(512, 2) mk_fwd(Params p) {
;     ...
;     PHASE(2, 2, {
;         for (int it = VB(); it < 1088 + 1056; it += G) {
;             if (it < 1024) attn_prompt_item(lds, p, it, dry);
;             else if (it < 1088) attn_sample_item(lds, p, it - 1024, dry);
;             else gla_a_item(lds, p, it - 1088);
;         } });
.LBB0_716:
	s_sub_i32 s98, s73, 0x400
	s_cmp_lt_u32 s98, 64
	s_cselect_b32 s99, 0xc0, 0
	s_sub_i32 s98, s73, 0x4c0
	s_cmp_lt_u32 s98, 64
	s_cselect_b32 s99, 0xffffff40, s99
	s_add_i32 s73, s73, s99
	s_add_i32 s75, s75, s99
	s_add_i32 s28, s28, s99
	s_lshl_b32 s99, s99, 1
	s_add_i32 s29, s29, s99
	s_add_i32 s73, s73, s34
	s_add_i32 s75, s75, s34
	s_add_i32 s28, s28, s34
	s_add_i32 s29, s29, s30
	s_cmpk_lt_i32 s73, 0x860
	s_cbranch_scc0 .LBB0_838
.LBB0_717:
	s_sub_i32 s98, s73, 0x400
	s_cmp_lt_u32 s98, 64
	s_cselect_b32 s99, 0xc0, 0
	s_sub_i32 s98, s73, 0x4c0
	s_cmp_lt_u32 s98, 64
	s_cselect_b32 s99, 0xffffff40, s99
	s_add_i32 s73, s73, s99
	s_add_i32 s75, s75, s99
	s_add_i32 s28, s28, s99
	s_lshl_b32 s99, s99, 1
	s_add_i32 s29, s29, s99
	s_cmpk_gt_i32 s73, 0x3ff
	s_mov_b64 s[0:1], -1
	s_cbranch_scc0 .LBB0_812
	s_cmpk_gt_u32 s73, 0x43f
	s_cbranch_scc0 .LBB0_780
	s_add_i32 s5, s73, 0xfffffbc0
	s_cmpk_gt_u32 s5, 0x3ff
	s_cselect_b64 s[0:1], -1, 0
	s_cmpk_lt_u32 s5, 0x400
	s_cselect_b64 s[6:7], -1, 0
	s_mov_b64 s[2:3], -1
	s_and_b64 vcc, exec, s[6:7]
	s_cbranch_vccz .LBB0_721
	s_lshl_b32 s2, s5, 4
	s_lshl_b32 s3, s5, 6
	s_and_b32 s2, s2, 0x3000
	s_and_b32 s3, s3, 0xfc0
	s_or_b32 s17, s2, s3
	s_mov_b64 s[2:3], 0
